# prep modulation GEMV k-loop unrolled by two with both halves' 16 weight loads in flight (on top of v45)
# baseline (speedup 1.0000x reference)
.LBB0_12:
	v_lshl_add_u64 v[42:43], v[36:37], 0, s[12:13]
	v_add_co_u32_e64 v72, s[4:5], s15, v42
	ds_read_b128 v[108:111], v47
	ds_read_b128 v[114:117], v47 offset:16
	ds_read_b128 v[122:125], v47 offset:32
	ds_read_b128 v[130:133], v47 offset:48
	ds_read_b128 v[2:5], v47 offset:4096
	ds_read_b128 v[6:9], v47 offset:4112
	ds_read_b128 v[118:121], v47 offset:8192
	ds_read_b128 v[126:129], v47 offset:8208
	ds_read_b128 v[18:21], v47 offset:12288
	ds_read_b128 v[10:13], v47 offset:12304
	ds_read_b128 v[22:25], v47 offset:16384
	ds_read_b128 v[14:17], v47 offset:16400
	ds_read_b128 v[26:29], v47 offset:4128
	ds_read_b128 v[48:51], v47 offset:4144
	ds_read_b128 v[134:137], v47 offset:8224
	ds_read_b128 v[138:141], v47 offset:8240
	ds_read_b128 v[52:55], v47 offset:12320
	ds_read_b128 v[56:59], v47 offset:12336
	ds_read_b128 v[60:63], v47 offset:16416
	ds_read_b128 v[64:67], v47 offset:16432
	v_addc_co_u32_e64 v73, s[4:5], 0, v43, s[4:5]
	v_add_co_u32_e64 v74, s[4:5], s16, v42
	global_load_dword v70, v[42:43], off
	s_nop 0
	v_addc_co_u32_e64 v75, s[4:5], 0, v43, s[4:5]
	v_add_co_u32_e64 v76, s[4:5], s17, v42
	s_waitcnt lgkmcnt(14)
	v_mov_b32_e32 v112, v116
	v_addc_co_u32_e64 v77, s[4:5], 0, v43, s[4:5]
	v_add_co_u32_e64 v78, s[4:5], s18, v42
	v_mov_b32_e32 v113, v8
	s_nop 0
	v_addc_co_u32_e64 v79, s[4:5], 0, v43, s[4:5]
	v_add_co_u32_e64 v80, s[4:5], s19, v42
	v_mov_b32_e32 v8, v117
	s_nop 0
	v_addc_co_u32_e64 v81, s[4:5], 0, v43, s[4:5]
	v_add_co_u32_e64 v82, s[4:5], s20, v42
	v_mov_b32_e32 v116, v122
	s_nop 0
	v_addc_co_u32_e64 v83, s[4:5], 0, v43, s[4:5]
	v_add_co_u32_e64 v84, s[4:5], s21, v42
	s_waitcnt lgkmcnt(7)
	v_mov_b32_e32 v117, v26
	v_addc_co_u32_e64 v85, s[4:5], 0, v43, s[4:5]
	v_add_co_u32_e64 v86, s[4:5], s22, v42
	v_mov_b32_e32 v26, v123
	s_nop 0
	v_addc_co_u32_e64 v87, s[4:5], 0, v43, s[4:5]
	v_add_co_u32_e64 v88, s[4:5], s23, v42
	s_waitcnt lgkmcnt(5)
	v_mov_b32_e32 v122, v136
	v_addc_co_u32_e64 v89, s[4:5], 0, v43, s[4:5]
	v_add_co_u32_e64 v90, s[4:5], s24, v42
	s_waitcnt lgkmcnt(3)
	v_mov_b32_e32 v123, v54
	v_addc_co_u32_e64 v91, s[4:5], 0, v43, s[4:5]
	v_add_co_u32_e64 v92, s[4:5], s25, v42
	v_mov_b32_e32 v54, v137
	s_nop 0
	v_addc_co_u32_e64 v93, s[4:5], 0, v43, s[4:5]
	v_add_co_u32_e64 v94, s[4:5], s26, v42
	s_add_u32 s12, s12, 0x60000
	s_nop 0
	v_addc_co_u32_e64 v95, s[4:5], 0, v43, s[4:5]
	v_add_co_u32_e64 v96, s[4:5], s27, v42
	s_addc_u32 s13, s13, 0
	s_nop 0
	v_addc_co_u32_e64 v97, s[4:5], 0, v43, s[4:5]
	v_add_co_u32_e64 v98, s[4:5], s28, v42
	v_add_u32_e32 v47, 64, v47
	s_nop 0
	v_addc_co_u32_e64 v99, s[4:5], 0, v43, s[4:5]
	v_add_co_u32_e64 v42, s[4:5], s29, v42
	s_cmp_eq_u32 s12, 0x600000
	s_nop 0
	v_addc_co_u32_e64 v43, s[4:5], 0, v43, s[4:5]
	global_load_dword v72, v[72:73], off
	s_nop 0
	global_load_dword v74, v[74:75], off
	s_nop 0
	global_load_dword v76, v[76:77], off
	s_nop 0
	global_load_dword v78, v[78:79], off
	s_nop 0
	global_load_dword v80, v[80:81], off
	s_nop 0
	global_load_dword v82, v[82:83], off
	s_nop 0
	global_load_dword v84, v[84:85], off
	s_nop 0
	global_load_dword v86, v[86:87], off
	s_nop 0
	global_load_dword v88, v[88:89], off
	s_nop 0
	global_load_dword v100, v[90:91], off
	global_load_dword v102, v[92:93], off
	s_nop 0
	global_load_dword v90, v[94:95], off
	global_load_dword v92, v[96:97], off
	global_load_dword v104, v[98:99], off
	global_load_dword v106, v[42:43], off
	v_mov_b32_e32 v148, v42
	v_mov_b32_e32 v149, v43
	v_mov_b32_e32 v150, v72
	v_mov_b32_e32 v151, v73
	v_mov_b32_e32 v152, v74
	v_mov_b32_e32 v153, v75
	v_mov_b32_e32 v154, v76
	v_mov_b32_e32 v155, v77
	v_mov_b32_e32 v156, v78
	v_mov_b32_e32 v157, v79
	v_mov_b32_e32 v158, v80
	v_mov_b32_e32 v159, v81
	v_mov_b32_e32 v160, v82
	v_mov_b32_e32 v161, v83
	v_mov_b32_e32 v162, v84
	v_mov_b32_e32 v163, v85
	v_mov_b32_e32 v164, v86
	v_mov_b32_e32 v165, v87
	v_mov_b32_e32 v166, v88
	v_mov_b32_e32 v167, v89
	v_mov_b32_e32 v168, v90
	v_mov_b32_e32 v169, v91
	v_mov_b32_e32 v170, v92
	v_mov_b32_e32 v171, v93
	v_mov_b32_e32 v172, v94
	v_mov_b32_e32 v173, v95
	v_mov_b32_e32 v174, v96
	v_mov_b32_e32 v175, v97
	v_mov_b32_e32 v176, v98
	v_mov_b32_e32 v177, v99
	v_lshl_add_u64 v[148:149], v[36:37], 0, s[12:13]
	v_add_co_u32_e64 v150, s[4:5], s15, v148
	v_addc_co_u32_e64 v151, s[4:5], 0, v149, s[4:5]
	v_add_co_u32_e64 v152, s[4:5], s16, v148
	global_load_dword v252, v[148:149], off
	v_addc_co_u32_e64 v153, s[4:5], 0, v149, s[4:5]
	v_add_co_u32_e64 v154, s[4:5], s17, v148
	v_addc_co_u32_e64 v155, s[4:5], 0, v149, s[4:5]
	v_add_co_u32_e64 v156, s[4:5], s18, v148
	v_addc_co_u32_e64 v157, s[4:5], 0, v149, s[4:5]
	v_add_co_u32_e64 v158, s[4:5], s19, v148
	v_addc_co_u32_e64 v159, s[4:5], 0, v149, s[4:5]
	v_add_co_u32_e64 v160, s[4:5], s20, v148
	v_addc_co_u32_e64 v161, s[4:5], 0, v149, s[4:5]
	v_add_co_u32_e64 v162, s[4:5], s21, v148
	v_addc_co_u32_e64 v163, s[4:5], 0, v149, s[4:5]
	v_add_co_u32_e64 v164, s[4:5], s22, v148
	v_addc_co_u32_e64 v165, s[4:5], 0, v149, s[4:5]
	v_add_co_u32_e64 v166, s[4:5], s23, v148
	v_addc_co_u32_e64 v167, s[4:5], 0, v149, s[4:5]
	v_add_co_u32_e64 v168, s[4:5], s24, v148
	v_addc_co_u32_e64 v169, s[4:5], 0, v149, s[4:5]
	v_add_co_u32_e64 v170, s[4:5], s25, v148
	v_addc_co_u32_e64 v171, s[4:5], 0, v149, s[4:5]
	v_add_co_u32_e64 v172, s[4:5], s26, v148
	v_addc_co_u32_e64 v173, s[4:5], 0, v149, s[4:5]
	v_add_co_u32_e64 v174, s[4:5], s27, v148
	v_addc_co_u32_e64 v175, s[4:5], 0, v149, s[4:5]
	v_add_co_u32_e64 v176, s[4:5], s28, v148
	v_addc_co_u32_e64 v177, s[4:5], 0, v149, s[4:5]
	v_add_co_u32_e64 v148, s[4:5], s29, v148
	v_addc_co_u32_e64 v149, s[4:5], 0, v149, s[4:5]
	global_load_dword v251, v[150:151], off
	global_load_dword v250, v[152:153], off
	global_load_dword v249, v[154:155], off
	global_load_dword v248, v[156:157], off
	global_load_dword v247, v[158:159], off
	global_load_dword v246, v[160:161], off
	global_load_dword v245, v[162:163], off
	global_load_dword v244, v[164:165], off
	global_load_dword v243, v[166:167], off
	global_load_dword v242, v[168:169], off
	global_load_dword v241, v[170:171], off
	global_load_dword v240, v[172:173], off
	global_load_dword v239, v[174:175], off
	global_load_dword v238, v[176:177], off
	global_load_dword v237, v[148:149], off
	v_mov_b32_e32 v42, v108
	v_mov_b32_e32 v43, v2
	v_mov_b32_e32 v94, v118
	v_mov_b32_e32 v95, v18
	v_mov_b32_e32 v2, v109
	v_mov_b32_e32 v18, v119
	v_mov_b32_e32 v96, v110
	v_mov_b32_e32 v97, v4
	v_mov_b32_e32 v98, v120
	v_mov_b32_e32 v99, v20
	v_mov_b32_e32 v4, v111
	s_waitcnt vmcnt(31)
	v_pk_fma_f32 v[38:39], v[70:71], v[42:43], v[38:39] op_sel_hi:[0,1,1]
	v_pk_fma_f32 v[40:41], v[70:71], v[94:95], v[40:41] op_sel_hi:[0,1,1]
	v_fmac_f32_e32 v46, v70, v22
	v_mov_b32_e32 v20, v121
	v_mov_b32_e32 v108, v114
	v_mov_b32_e32 v109, v6
	v_mov_b32_e32 v110, v126
	v_mov_b32_e32 v111, v10
	v_mov_b32_e32 v6, v115
	v_mov_b32_e32 v10, v127
	v_mov_b32_e32 v114, v128
	v_mov_b32_e32 v115, v12
	v_mov_b32_e32 v12, v129
	v_mov_b32_e32 v118, v134
	v_mov_b32_e32 v119, v52
	v_mov_b32_e32 v52, v135
	v_mov_b32_e32 v120, v124
	v_mov_b32_e32 v121, v28
	v_mov_b32_e32 v28, v125
	v_mov_b32_e32 v124, v130
	v_mov_b32_e32 v125, v48
	v_mov_b32_e32 v126, v138
	s_waitcnt lgkmcnt(2)
	v_mov_b32_e32 v127, v56
	v_mov_b32_e32 v48, v131
	v_mov_b32_e32 v56, v139
	v_mov_b32_e32 v128, v132
	v_mov_b32_e32 v129, v50
	v_mov_b32_e32 v130, v140
	v_mov_b32_e32 v131, v58
	v_mov_b32_e32 v50, v133
	v_mov_b32_e32 v58, v141
	s_waitcnt vmcnt(30)
	v_pk_fma_f32 v[2:3], v[72:73], v[2:3], v[38:39] op_sel_hi:[0,1,1]
	v_pk_fma_f32 v[18:19], v[72:73], v[18:19], v[40:41] op_sel_hi:[0,1,1]
	v_fmac_f32_e32 v46, v72, v23
	s_waitcnt vmcnt(29)
	v_pk_fma_f32 v[2:3], v[74:75], v[96:97], v[2:3] op_sel_hi:[0,1,1]
	v_pk_fma_f32 v[18:19], v[74:75], v[98:99], v[18:19] op_sel_hi:[0,1,1]
	v_fmac_f32_e32 v46, v74, v24
	s_waitcnt vmcnt(28)
	v_pk_fma_f32 v[2:3], v[76:77], v[4:5], v[2:3] op_sel_hi:[0,1,1]
	v_pk_fma_f32 v[4:5], v[76:77], v[20:21], v[18:19] op_sel_hi:[0,1,1]
	v_fmac_f32_e32 v46, v76, v25
	s_waitcnt vmcnt(27)
	v_pk_fma_f32 v[2:3], v[78:79], v[108:109], v[2:3] op_sel_hi:[0,1,1]
	v_pk_fma_f32 v[4:5], v[78:79], v[110:111], v[4:5] op_sel_hi:[0,1,1]
	v_fmac_f32_e32 v46, v78, v14
	s_waitcnt vmcnt(26)
	v_pk_fma_f32 v[2:3], v[80:81], v[6:7], v[2:3] op_sel_hi:[0,1,1]
	v_pk_fma_f32 v[4:5], v[80:81], v[10:11], v[4:5] op_sel_hi:[0,1,1]
	v_fmac_f32_e32 v46, v80, v15
	s_waitcnt vmcnt(25)
	v_pk_fma_f32 v[2:3], v[82:83], v[112:113], v[2:3] op_sel_hi:[0,1,1]
	v_pk_fma_f32 v[4:5], v[82:83], v[114:115], v[4:5] op_sel_hi:[0,1,1]
	v_fmac_f32_e32 v46, v82, v16
	s_waitcnt vmcnt(24)
	v_pk_fma_f32 v[2:3], v[84:85], v[8:9], v[2:3] op_sel_hi:[0,1,1]
	v_pk_fma_f32 v[4:5], v[84:85], v[12:13], v[4:5] op_sel_hi:[0,1,1]
	v_fmac_f32_e32 v46, v84, v17
	s_waitcnt vmcnt(23)
	v_pk_fma_f32 v[2:3], v[86:87], v[116:117], v[2:3] op_sel_hi:[0,1,1]
	v_pk_fma_f32 v[4:5], v[86:87], v[118:119], v[4:5] op_sel_hi:[0,1,1]
	s_waitcnt lgkmcnt(1)
	v_fmac_f32_e32 v46, v86, v60
	s_waitcnt vmcnt(22)
	v_pk_fma_f32 v[2:3], v[88:89], v[26:27], v[2:3] op_sel_hi:[0,1,1]
	v_pk_fma_f32 v[4:5], v[88:89], v[52:53], v[4:5] op_sel_hi:[0,1,1]
	v_fmac_f32_e32 v46, v88, v61
	s_waitcnt vmcnt(21)
	v_pk_fma_f32 v[2:3], v[100:101], v[120:121], v[2:3] op_sel_hi:[0,1,1]
	v_pk_fma_f32 v[4:5], v[100:101], v[122:123], v[4:5] op_sel_hi:[0,1,1]
	v_fmac_f32_e32 v46, v100, v62
	s_waitcnt vmcnt(20)
	v_pk_fma_f32 v[2:3], v[102:103], v[28:29], v[2:3] op_sel_hi:[0,1,1]
	v_pk_fma_f32 v[4:5], v[102:103], v[54:55], v[4:5] op_sel_hi:[0,1,1]
	v_fmac_f32_e32 v46, v102, v63
	s_waitcnt vmcnt(19)
	v_pk_fma_f32 v[2:3], v[90:91], v[124:125], v[2:3] op_sel_hi:[0,1,1]
	v_pk_fma_f32 v[4:5], v[90:91], v[126:127], v[4:5] op_sel_hi:[0,1,1]
	s_waitcnt lgkmcnt(0)
	v_fmac_f32_e32 v46, v90, v64
	s_waitcnt vmcnt(18)
	v_pk_fma_f32 v[2:3], v[92:93], v[48:49], v[2:3] op_sel_hi:[0,1,1]
	v_pk_fma_f32 v[4:5], v[92:93], v[56:57], v[4:5] op_sel_hi:[0,1,1]
	v_fmac_f32_e32 v46, v92, v65
	s_waitcnt vmcnt(17)
	v_pk_fma_f32 v[2:3], v[104:105], v[128:129], v[2:3] op_sel_hi:[0,1,1]
	v_pk_fma_f32 v[4:5], v[104:105], v[130:131], v[4:5] op_sel_hi:[0,1,1]
	v_fmac_f32_e32 v46, v104, v66
	s_waitcnt vmcnt(16)
	v_pk_fma_f32 v[38:39], v[106:107], v[50:51], v[2:3] op_sel_hi:[0,1,1]
	v_pk_fma_f32 v[40:41], v[106:107], v[58:59], v[4:5] op_sel_hi:[0,1,1]
	v_fmac_f32_e32 v46, v106, v67
	v_lshl_add_u64 v[42:43], v[36:37], 0, s[12:13]
	v_add_co_u32_e64 v72, s[4:5], s15, v42
	ds_read_b128 v[108:111], v47
	ds_read_b128 v[114:117], v47 offset:16
	ds_read_b128 v[122:125], v47 offset:32
	ds_read_b128 v[130:133], v47 offset:48
	ds_read_b128 v[2:5], v47 offset:4096
	ds_read_b128 v[6:9], v47 offset:4112
	ds_read_b128 v[118:121], v47 offset:8192
	ds_read_b128 v[126:129], v47 offset:8208
	ds_read_b128 v[18:21], v47 offset:12288
	ds_read_b128 v[10:13], v47 offset:12304
	ds_read_b128 v[22:25], v47 offset:16384
	ds_read_b128 v[14:17], v47 offset:16400
	ds_read_b128 v[26:29], v47 offset:4128
	ds_read_b128 v[48:51], v47 offset:4144
	ds_read_b128 v[134:137], v47 offset:8224
	ds_read_b128 v[138:141], v47 offset:8240
	ds_read_b128 v[52:55], v47 offset:12320
	ds_read_b128 v[56:59], v47 offset:12336
	ds_read_b128 v[60:63], v47 offset:16416
	ds_read_b128 v[64:67], v47 offset:16432
	v_addc_co_u32_e64 v73, s[4:5], 0, v43, s[4:5]
	v_add_co_u32_e64 v74, s[4:5], s16, v42
	s_waitcnt vmcnt(15)
	s_nop 1
	v_mov_b32_e32 v70, v252
	s_nop 0
	v_addc_co_u32_e64 v75, s[4:5], 0, v43, s[4:5]
	v_add_co_u32_e64 v76, s[4:5], s17, v42
	s_waitcnt lgkmcnt(14)
	v_mov_b32_e32 v112, v116
	v_addc_co_u32_e64 v77, s[4:5], 0, v43, s[4:5]
	v_add_co_u32_e64 v78, s[4:5], s18, v42
	v_mov_b32_e32 v113, v8
	s_nop 0
	v_addc_co_u32_e64 v79, s[4:5], 0, v43, s[4:5]
	v_add_co_u32_e64 v80, s[4:5], s19, v42
	v_mov_b32_e32 v8, v117
	s_nop 0
	v_addc_co_u32_e64 v81, s[4:5], 0, v43, s[4:5]
	v_add_co_u32_e64 v82, s[4:5], s20, v42
	v_mov_b32_e32 v116, v122
	s_nop 0
	v_addc_co_u32_e64 v83, s[4:5], 0, v43, s[4:5]
	v_add_co_u32_e64 v84, s[4:5], s21, v42
	s_waitcnt lgkmcnt(7)
	v_mov_b32_e32 v117, v26
	v_addc_co_u32_e64 v85, s[4:5], 0, v43, s[4:5]
	v_add_co_u32_e64 v86, s[4:5], s22, v42
	v_mov_b32_e32 v26, v123
	s_nop 0
	v_addc_co_u32_e64 v87, s[4:5], 0, v43, s[4:5]
	v_add_co_u32_e64 v88, s[4:5], s23, v42
	s_waitcnt lgkmcnt(5)
	v_mov_b32_e32 v122, v136
	v_addc_co_u32_e64 v89, s[4:5], 0, v43, s[4:5]
	v_add_co_u32_e64 v90, s[4:5], s24, v42
	s_waitcnt lgkmcnt(3)
	v_mov_b32_e32 v123, v54
	v_addc_co_u32_e64 v91, s[4:5], 0, v43, s[4:5]
	v_add_co_u32_e64 v92, s[4:5], s25, v42
	v_mov_b32_e32 v54, v137
	s_nop 0
	v_addc_co_u32_e64 v93, s[4:5], 0, v43, s[4:5]
	v_add_co_u32_e64 v94, s[4:5], s26, v42
	s_add_u32 s12, s12, 0x60000
	s_nop 0
	v_addc_co_u32_e64 v95, s[4:5], 0, v43, s[4:5]
	v_add_co_u32_e64 v96, s[4:5], s27, v42
	s_addc_u32 s13, s13, 0
	s_nop 0
	v_addc_co_u32_e64 v97, s[4:5], 0, v43, s[4:5]
	v_add_co_u32_e64 v98, s[4:5], s28, v42
	v_add_u32_e32 v47, 64, v47
	s_nop 0
	v_addc_co_u32_e64 v99, s[4:5], 0, v43, s[4:5]
	v_add_co_u32_e64 v42, s[4:5], s29, v42
	s_cmp_eq_u32 s12, 0x600000
	s_nop 0
	v_addc_co_u32_e64 v43, s[4:5], 0, v43, s[4:5]
	s_waitcnt vmcnt(14)
	s_nop 1
	v_mov_b32_e32 v72, v251
	s_nop 0
	s_waitcnt vmcnt(13)
	s_nop 1
	v_mov_b32_e32 v74, v250
	s_nop 0
	s_waitcnt vmcnt(12)
	s_nop 1
	v_mov_b32_e32 v76, v249
	s_nop 0
	s_waitcnt vmcnt(11)
	s_nop 1
	v_mov_b32_e32 v78, v248
	s_nop 0
	s_waitcnt vmcnt(10)
	s_nop 1
	v_mov_b32_e32 v80, v247
	s_nop 0
	s_waitcnt vmcnt(9)
	s_nop 1
	v_mov_b32_e32 v82, v246
	s_nop 0
	s_waitcnt vmcnt(8)
	s_nop 1
	v_mov_b32_e32 v84, v245
	s_nop 0
	s_waitcnt vmcnt(7)
	s_nop 1
	v_mov_b32_e32 v86, v244
	s_nop 0
	s_waitcnt vmcnt(6)
	s_nop 1
	v_mov_b32_e32 v88, v243
	s_nop 0
	s_waitcnt vmcnt(5)
	s_nop 1
	v_mov_b32_e32 v100, v242
	s_waitcnt vmcnt(4)
	s_nop 1
	v_mov_b32_e32 v102, v241
	s_nop 0
	s_waitcnt vmcnt(3)
	s_nop 1
	v_mov_b32_e32 v90, v240
	s_waitcnt vmcnt(2)
	s_nop 1
	v_mov_b32_e32 v92, v239
	s_waitcnt vmcnt(1)
	s_nop 1
	v_mov_b32_e32 v104, v238
	s_waitcnt vmcnt(0)
	s_nop 1
	v_mov_b32_e32 v106, v237
	v_mov_b32_e32 v42, v108
	v_mov_b32_e32 v43, v2
	v_mov_b32_e32 v94, v118
	v_mov_b32_e32 v95, v18
	v_mov_b32_e32 v2, v109
	v_mov_b32_e32 v18, v119
	v_mov_b32_e32 v96, v110
	v_mov_b32_e32 v97, v4
	v_mov_b32_e32 v98, v120
	v_mov_b32_e32 v99, v20
	v_mov_b32_e32 v4, v111
	s_waitcnt vmcnt(15)
	v_pk_fma_f32 v[38:39], v[70:71], v[42:43], v[38:39] op_sel_hi:[0,1,1]
	v_pk_fma_f32 v[40:41], v[70:71], v[94:95], v[40:41] op_sel_hi:[0,1,1]
	v_fmac_f32_e32 v46, v70, v22
	v_mov_b32_e32 v20, v121
	v_mov_b32_e32 v108, v114
	v_mov_b32_e32 v109, v6
	v_mov_b32_e32 v110, v126
	v_mov_b32_e32 v111, v10
	v_mov_b32_e32 v6, v115
	v_mov_b32_e32 v10, v127
	v_mov_b32_e32 v114, v128
	v_mov_b32_e32 v115, v12
	v_mov_b32_e32 v12, v129
	v_mov_b32_e32 v118, v134
	v_mov_b32_e32 v119, v52
	v_mov_b32_e32 v52, v135
	v_mov_b32_e32 v120, v124
	v_mov_b32_e32 v121, v28
	v_mov_b32_e32 v28, v125
	v_mov_b32_e32 v124, v130
	v_mov_b32_e32 v125, v48
	v_mov_b32_e32 v126, v138
	s_waitcnt lgkmcnt(2)
	v_mov_b32_e32 v127, v56
	v_mov_b32_e32 v48, v131
	v_mov_b32_e32 v56, v139
	v_mov_b32_e32 v128, v132
	v_mov_b32_e32 v129, v50
	v_mov_b32_e32 v130, v140
	v_mov_b32_e32 v131, v58
	v_mov_b32_e32 v50, v133
	v_mov_b32_e32 v58, v141
	s_waitcnt vmcnt(14)
	v_pk_fma_f32 v[2:3], v[72:73], v[2:3], v[38:39] op_sel_hi:[0,1,1]
	v_pk_fma_f32 v[18:19], v[72:73], v[18:19], v[40:41] op_sel_hi:[0,1,1]
	v_fmac_f32_e32 v46, v72, v23
	s_waitcnt vmcnt(13)
	v_pk_fma_f32 v[2:3], v[74:75], v[96:97], v[2:3] op_sel_hi:[0,1,1]
	v_pk_fma_f32 v[18:19], v[74:75], v[98:99], v[18:19] op_sel_hi:[0,1,1]
	v_fmac_f32_e32 v46, v74, v24
	s_waitcnt vmcnt(12)
	v_pk_fma_f32 v[2:3], v[76:77], v[4:5], v[2:3] op_sel_hi:[0,1,1]
	v_pk_fma_f32 v[4:5], v[76:77], v[20:21], v[18:19] op_sel_hi:[0,1,1]
	v_fmac_f32_e32 v46, v76, v25
	s_waitcnt vmcnt(11)
	v_pk_fma_f32 v[2:3], v[78:79], v[108:109], v[2:3] op_sel_hi:[0,1,1]
	v_pk_fma_f32 v[4:5], v[78:79], v[110:111], v[4:5] op_sel_hi:[0,1,1]
	v_fmac_f32_e32 v46, v78, v14
	s_waitcnt vmcnt(10)
	v_pk_fma_f32 v[2:3], v[80:81], v[6:7], v[2:3] op_sel_hi:[0,1,1]
	v_pk_fma_f32 v[4:5], v[80:81], v[10:11], v[4:5] op_sel_hi:[0,1,1]
	v_fmac_f32_e32 v46, v80, v15
	s_waitcnt vmcnt(9)
	v_pk_fma_f32 v[2:3], v[82:83], v[112:113], v[2:3] op_sel_hi:[0,1,1]
	v_pk_fma_f32 v[4:5], v[82:83], v[114:115], v[4:5] op_sel_hi:[0,1,1]
	v_fmac_f32_e32 v46, v82, v16
	s_waitcnt vmcnt(8)
	v_pk_fma_f32 v[2:3], v[84:85], v[8:9], v[2:3] op_sel_hi:[0,1,1]
	v_pk_fma_f32 v[4:5], v[84:85], v[12:13], v[4:5] op_sel_hi:[0,1,1]
	v_fmac_f32_e32 v46, v84, v17
	s_waitcnt vmcnt(7)
	v_pk_fma_f32 v[2:3], v[86:87], v[116:117], v[2:3] op_sel_hi:[0,1,1]
	v_pk_fma_f32 v[4:5], v[86:87], v[118:119], v[4:5] op_sel_hi:[0,1,1]
	s_waitcnt lgkmcnt(1)
	v_fmac_f32_e32 v46, v86, v60
	s_waitcnt vmcnt(6)
	v_pk_fma_f32 v[2:3], v[88:89], v[26:27], v[2:3] op_sel_hi:[0,1,1]
	v_pk_fma_f32 v[4:5], v[88:89], v[52:53], v[4:5] op_sel_hi:[0,1,1]
	v_fmac_f32_e32 v46, v88, v61
	s_waitcnt vmcnt(5)
	v_pk_fma_f32 v[2:3], v[100:101], v[120:121], v[2:3] op_sel_hi:[0,1,1]
	v_pk_fma_f32 v[4:5], v[100:101], v[122:123], v[4:5] op_sel_hi:[0,1,1]
	v_fmac_f32_e32 v46, v100, v62
	s_waitcnt vmcnt(4)
	v_pk_fma_f32 v[2:3], v[102:103], v[28:29], v[2:3] op_sel_hi:[0,1,1]
	v_pk_fma_f32 v[4:5], v[102:103], v[54:55], v[4:5] op_sel_hi:[0,1,1]
	v_fmac_f32_e32 v46, v102, v63
	s_waitcnt vmcnt(3)
	v_pk_fma_f32 v[2:3], v[90:91], v[124:125], v[2:3] op_sel_hi:[0,1,1]
	v_pk_fma_f32 v[4:5], v[90:91], v[126:127], v[4:5] op_sel_hi:[0,1,1]
	s_waitcnt lgkmcnt(0)
	v_fmac_f32_e32 v46, v90, v64
	s_waitcnt vmcnt(2)
	v_pk_fma_f32 v[2:3], v[92:93], v[48:49], v[2:3] op_sel_hi:[0,1,1]
	v_pk_fma_f32 v[4:5], v[92:93], v[56:57], v[4:5] op_sel_hi:[0,1,1]
	v_fmac_f32_e32 v46, v92, v65
	s_waitcnt vmcnt(1)
	v_pk_fma_f32 v[2:3], v[104:105], v[128:129], v[2:3] op_sel_hi:[0,1,1]
	v_pk_fma_f32 v[4:5], v[104:105], v[130:131], v[4:5] op_sel_hi:[0,1,1]
	v_fmac_f32_e32 v46, v104, v66
	s_waitcnt vmcnt(0)
	v_pk_fma_f32 v[38:39], v[106:107], v[50:51], v[2:3] op_sel_hi:[0,1,1]
	v_pk_fma_f32 v[40:41], v[106:107], v[58:59], v[4:5] op_sel_hi:[0,1,1]
	v_fmac_f32_e32 v46, v106, v67
	s_cbranch_scc0 .LBB0_12
	ds_write2st64_b32 v30, v38, v39 offset0:80 offset1:81
	ds_write2st64_b32 v30, v40, v41 offset0:82 offset1:83
	ds_write_b32 v30, v46 offset:21504
	s_waitcnt lgkmcnt(0)
	s_barrier
	s_and_saveexec_b64 s[12:13], vcc
	s_cbranch_execz .LBB0_10
	s_mul_i32 s4, s31, 0x1800
	s_add_i32 s4, s4, s10
	v_accvgpr_read_b32 v2, a202
	v_or_b32_e32 v2, s4, v2
	s_mul_i32 s4, s31, 0x1e000
	s_mul_hi_i32 s5, s31, 0x1e000
	s_add_u32 s4, s4, s8
	v_ashrrev_i32_e32 v3, 31, v2
	s_addc_u32 s5, s5, s9
	v_lshl_add_u64 v[2:3], v[2:3], 2, s[6:7]
	v_lshl_add_u64 v[4:5], v[34:35], 0, s[4:5]
	s_mov_b64 s[8:9], 0
	v_mov_b32_e32 v6, v45
	v_mov_b32_e32 v7, v142
